# best4 + nt sc1 on attention output stores
# speedup vs baseline: 1.0223x; 1.0223x over previous
; __device__ __forceinline__ float bf_lo(unsigned w) { return __uint_as_float(w << 16); }
; __device__ __forceinline__ float silu_f(float v) { return v * __builtin_amdgcn_rcpf(1.0f + __builtin_amdgcn_exp2f(-1.4426950408889634f * v)); }
; __device__ __forceinline__ float bf_hi(unsigned w) { return __uint_as_float(w & 0xffff0000u); }
; __device__ __forceinline__ int crow(int r, int hi) { return (r & 3) + 8 * (r >> 2) + 4 * hi; }
; __device__ __forceinline__ int crow(int r,int hi){return (r&3)+8*(r>>2)+4*hi;}
; __device__ __forceinline__ unsigned cvtpk_s(float lo,float hi){f32x2_t v={lo,hi};bf16x2_t b=__builtin_convertvector(v,bf16x2_t);return __builtin_bit_cast(unsigned,b);}
; template<int THRL> __device__ __forceinline__ void attn_unit(int b,int h,int qb,const bf16*Q,const bf16*__restrict__ K,const bf16*__restrict__ V,const unsigned short*GB,unsigned short*Y,const float*Fcum,int ts,char*shm){
;     ...
;   {auto rr=__builtin_amdgcn_permlane32_swap(__float_as_uint(l_reg),__float_as_uint(l_reg),false,false);l_reg=__uint_as_float(rr[0])+__uint_as_float(rr[1]);}
;   if(hi==0)wsf[32+r32]=l_reg;asm volatile("s_waitcnt lgkmcnt(0)":::"memory");
;   float rli[16];
;   #pragma unroll
;   for(int r=0;r<16;++r)rli[r]=__builtin_amdgcn_rcpf(wsf[32+crow(r,hi)]);
;   { bf16*stg=(bf16*)(shm+LDS_OST)+wid*2048;
;     #pragma unroll
;     for(int r=0;r<16;++r){const int orow=crow(r,hi);
;       #pragma unroll
;       for(int d0=0;d0<2;++d0)stg[orow*64+d0*32+r32]=__float2bfloat16(o[d0][r]*rli[r]);}
;     asm volatile("s_waitcnt lgkmcnt(0)":::"memory");
;     const long grow0=rowbase+q0+wid*QBLK;
;     #pragma unroll
;     for(int i=0;i<4;++i){const int row=i*8+(lane>>3),ch=lane&7; const u32x4 v=*(const u32x4*)(stg+row*64+ch*8);
;       const u32x4 g=*(const u32x4*)(shm+LDS_G+wid*4096+i*1024+lane*16); u32x4 w;
;       w.x=cvtpk_s(bf_lo(v.x)*silu_f(bf_lo(g.x)),bf_hi(v.x)*silu_f(bf_hi(g.x))); w.y=cvtpk_s(bf_lo(v.y)*silu_f(bf_lo(g.y)),bf_hi(v.y)*silu_f(bf_hi(g.y)));
.LBB0_197:
	s_or_b64 exec, exec, s[38:39]
	s_waitcnt lgkmcnt(0)
	ds_read_b128 v[32:35], v236 offset:49280
	ds_read_b128 v[36:39], v236 offset:49312
	v_lshlrev_b32_e32 v49, 9, v231
	v_lshlrev_b32_e32 v50, 1, v230
	v_add3_u32 v49, s68, v49, v50
	s_waitcnt lgkmcnt(1)
	v_rcp_f32_e32 v40, v32
	v_rcp_f32_e32 v41, v33
	v_rcp_f32_e32 v42, v34
	v_rcp_f32_e32 v43, v35
	v_mul_f32_e32 v0, v0, v40
	v_mul_f32_e32 v16, v16, v40
	v_cvt_pk_bf16_f32 v0, v0, s0
	s_waitcnt lgkmcnt(0)
	v_rcp_f32_e32 v44, v36
	ds_read_b128 v[32:35], v236 offset:49344
	v_rcp_f32_e32 v45, v37
	v_rcp_f32_e32 v46, v38
	v_rcp_f32_e32 v47, v39
	ds_read_b128 v[36:39], v236 offset:49376
	v_lshlrev_b32_e32 v48, 7, v232
	v_cvt_pk_bf16_f32 v16, v16, s0
	ds_write_b16 v49, v0 offset:51264
	v_mul_f32_e32 v0, v17, v41
	ds_write_b16 v49, v16 offset:51200
	v_cvt_pk_bf16_f32 v0, v0, s0
	v_add3_u32 v16, s68, v48, v50
	ds_write_b16 v16, v0 offset:51328
	v_mul_f32_e32 v0, v1, v41
	v_cvt_pk_bf16_f32 v0, v0, s0
	ds_write_b16 v16, v0 offset:51392
	v_mul_f32_e32 v0, v18, v42
	v_cvt_pk_bf16_f32 v0, v0, s0
	ds_write_b16 v16, v0 offset:51456
	v_mul_f32_e32 v0, v2, v42
	v_cvt_pk_bf16_f32 v0, v0, s0
	ds_write_b16 v16, v0 offset:51520
	v_mul_f32_e32 v0, v19, v43
	v_cvt_pk_bf16_f32 v0, v0, s0
	ds_write_b16 v16, v0 offset:51584
	v_mul_f32_e32 v0, v3, v43
	v_cvt_pk_bf16_f32 v0, v0, s0
	ds_write_b16 v16, v0 offset:51648
	v_mul_f32_e32 v0, v20, v44
	v_cvt_pk_bf16_f32 v0, v0, s0
	ds_write_b16 v16, v0 offset:52224
	v_mul_f32_e32 v0, v4, v44
	v_cvt_pk_bf16_f32 v0, v0, s0
	ds_write_b16 v16, v0 offset:52288
	v_mul_f32_e32 v0, v21, v45
	v_cvt_pk_bf16_f32 v0, v0, s0
	ds_write_b16 v16, v0 offset:52352
	v_mul_f32_e32 v0, v5, v45
	v_cvt_pk_bf16_f32 v0, v0, s0
	ds_write_b16 v16, v0 offset:52416
	v_mul_f32_e32 v0, v22, v46
	v_cvt_pk_bf16_f32 v0, v0, s0
	ds_write_b16 v16, v0 offset:52480
	v_mul_f32_e32 v0, v6, v46
	v_cvt_pk_bf16_f32 v0, v0, s0
	s_waitcnt lgkmcnt(14)
	v_rcp_f32_e32 v32, v32
	ds_write_b16 v16, v0 offset:52544
	v_mul_f32_e32 v0, v23, v47
	v_cvt_pk_bf16_f32 v0, v0, s0
	ds_write_b16 v16, v0 offset:52608
	v_mul_f32_e32 v0, v7, v47
	v_cvt_pk_bf16_f32 v0, v0, s0
	v_rcp_f32_e32 v33, v33
	ds_write_b16 v16, v0 offset:52672
	v_mul_f32_e32 v0, v24, v32
	v_cvt_pk_bf16_f32 v0, v0, s0
	ds_write_b16 v16, v0 offset:53248
	v_mul_f32_e32 v0, v8, v32
	v_cvt_pk_bf16_f32 v0, v0, s0
	v_rcp_f32_e32 v34, v34
	ds_write_b16 v16, v0 offset:53312
	v_mul_f32_e32 v0, v25, v33
	v_cvt_pk_bf16_f32 v0, v0, s0
	ds_write_b16 v16, v0 offset:53376
	v_mul_f32_e32 v0, v9, v33
	v_cvt_pk_bf16_f32 v0, v0, s0
	v_rcp_f32_e32 v35, v35
	ds_write_b16 v16, v0 offset:53440
	v_mul_f32_e32 v0, v26, v34
	v_cvt_pk_bf16_f32 v0, v0, s0
	ds_write_b16 v16, v0 offset:53504
	v_mul_f32_e32 v0, v10, v34
	v_cvt_pk_bf16_f32 v0, v0, s0
	s_waitcnt lgkmcnt(14)
	v_rcp_f32_e32 v36, v36
	ds_write_b16 v16, v0 offset:53568
	v_mul_f32_e32 v0, v27, v35
	v_cvt_pk_bf16_f32 v0, v0, s0
	ds_write_b16 v16, v0 offset:53632
	v_mul_f32_e32 v0, v11, v35
	v_cvt_pk_bf16_f32 v0, v0, s0
	v_rcp_f32_e32 v37, v37
	ds_write_b16 v16, v0 offset:53696
	v_mul_f32_e32 v0, v28, v36
	v_cvt_pk_bf16_f32 v0, v0, s0
	ds_write_b16 v16, v0 offset:54272
	v_mul_f32_e32 v0, v12, v36
	v_cvt_pk_bf16_f32 v0, v0, s0
	v_rcp_f32_e32 v38, v38
	ds_write_b16 v16, v0 offset:54336
	v_mul_f32_e32 v0, v29, v37
	v_cvt_pk_bf16_f32 v0, v0, s0
	ds_write_b16 v16, v0 offset:54400
	v_mul_f32_e32 v0, v13, v37
	v_cvt_pk_bf16_f32 v0, v0, s0
	v_rcp_f32_e32 v39, v39
	ds_write_b16 v16, v0 offset:54464
	v_mul_f32_e32 v0, v30, v38
	v_cvt_pk_bf16_f32 v0, v0, s0
	ds_write_b16 v16, v0 offset:54528
	v_mul_f32_e32 v0, v14, v38
	v_cvt_pk_bf16_f32 v0, v0, s0
	ds_write_b16 v16, v0 offset:54592
	v_mul_f32_e32 v0, v31, v39
	v_cvt_pk_bf16_f32 v0, v0, s0
	ds_write_b16 v16, v0 offset:54656
	v_mul_f32_e32 v0, v15, v39
	v_cvt_pk_bf16_f32 v0, v0, s0
	ds_write_b16 v16, v0 offset:54720
	v_lshl_add_u32 v0, v229, 4, s68
	s_waitcnt lgkmcnt(0)
	v_add_u32_e32 v22, 0x18800, v0
	ds_read_b128 v[0:3], v22
	ds_read_b128 v[4:7], v22 offset:1024
	v_add_u32_e32 v23, s68, v96
	v_lshl_add_u32 v8, v211, 7, v23
	v_or_b32_e32 v24, 8, v211
	s_waitcnt lgkmcnt(1)
	v_lshlrev_b32_e32 v16, 16, v0
	v_and_b32_e32 v17, 0xffff0000, v0
	v_mul_f32_e32 v0, 0xbfb8aa3b, v16
	v_exp_f32_e32 v0, v0
	v_mul_f32_e32 v9, 0xbfb8aa3b, v17
	v_exp_f32_e32 v12, v9
	ds_read_b128 v[8:11], v8 offset:51200
	v_add_f32_e32 v0, 1.0, v0
	v_rcp_f32_e32 v18, v0
	v_add_f32_e32 v0, 1.0, v12
	v_rcp_f32_e32 v19, v0
	v_lshl_add_u32 v0, v24, 7, v23
	ds_read_b128 v[12:15], v0 offset:51200
	s_waitcnt lgkmcnt(1)
; __device__ __forceinline__ float bf_lo(unsigned w) { return __uint_as_float(w << 16); }
; __device__ __forceinline__ float silu_f(float v) { return v * __builtin_amdgcn_rcpf(1.0f + __builtin_amdgcn_exp2f(-1.4426950408889634f * v)); }
; __device__ __forceinline__ float bf_hi(unsigned w) { return __uint_as_float(w & 0xffff0000u); }
; __device__ __forceinline__ unsigned cvtpk_s(float lo,float hi){f32x2_t v={lo,hi};bf16x2_t b=__builtin_convertvector(v,bf16x2_t);return __builtin_bit_cast(unsigned,b);}
; template<int THRL> __device__ __forceinline__ void attn_unit(int b,int h,int qb,const bf16*Q,const bf16*__restrict__ K,const bf16*__restrict__ V,const unsigned short*GB,unsigned short*Y,const float*Fcum,int ts,char*shm){
;     ...
;     #pragma unroll
;     for(int i=0;i<4;++i){const int row=i*8+(lane>>3),ch=lane&7; const u32x4 v=*(const u32x4*)(stg+row*64+ch*8);
;       const u32x4 g=*(const u32x4*)(shm+LDS_G+wid*4096+i*1024+lane*16); u32x4 w;
;       w.x=cvtpk_s(bf_lo(v.x)*silu_f(bf_lo(g.x)),bf_hi(v.x)*silu_f(bf_hi(g.x))); w.y=cvtpk_s(bf_lo(v.y)*silu_f(bf_lo(g.y)),bf_hi(v.y)*silu_f(bf_hi(g.y)));
;       w.z=cvtpk_s(bf_lo(v.z)*silu_f(bf_lo(g.z)),bf_hi(v.z)*silu_f(bf_hi(g.z))); w.w=cvtpk_s(bf_lo(v.w)*silu_f(bf_lo(g.w)),bf_hi(v.w)*silu_f(bf_hi(g.w)));
;       *(u32x4*)(Y+(grow0+row)*1024+256+h*D+ch*8)=w;} }
	v_lshlrev_b32_e32 v20, 16, v8
	v_pk_mul_f32 v[16:17], v[18:19], v[16:17]
	v_lshlrev_b32_e32 v18, 16, v1
	v_and_b32_e32 v19, 0xffff0000, v1
	v_mul_f32_e32 v0, 0xbfb8aa3b, v18
	v_and_b32_e32 v21, 0xffff0000, v8
	v_exp_f32_e32 v8, v0
	v_mul_f32_e32 v0, 0xbfb8aa3b, v19
	v_exp_f32_e32 v25, v0
	v_pk_mul_f32 v[0:1], v[16:17], v[20:21]
	v_add_f32_e32 v8, 1.0, v8
	v_rcp_f32_e32 v16, v8
	v_add_f32_e32 v8, 1.0, v25
	v_rcp_f32_e32 v17, v8
	v_cvt_pk_bf16_f32 v0, v0, v1
	v_lshlrev_b32_e32 v8, 16, v9
	v_and_b32_e32 v9, 0xffff0000, v9
	v_pk_mul_f32 v[16:17], v[16:17], v[18:19]
	v_lshlrev_b32_e32 v18, 16, v2
	v_and_b32_e32 v19, 0xffff0000, v2
	v_mul_f32_e32 v1, 0xbfb8aa3b, v18
	v_exp_f32_e32 v1, v1
	v_mul_f32_e32 v2, 0xbfb8aa3b, v19
	v_exp_f32_e32 v2, v2
	v_pk_mul_f32 v[8:9], v[16:17], v[8:9]
	v_add_f32_e32 v1, 1.0, v1
	v_rcp_f32_e32 v16, v1
	v_add_f32_e32 v1, 1.0, v2
	v_rcp_f32_e32 v17, v1
	v_cvt_pk_bf16_f32 v1, v8, v9
	v_lshlrev_b32_e32 v8, 16, v10
	v_and_b32_e32 v9, 0xffff0000, v10
	v_pk_mul_f32 v[16:17], v[16:17], v[18:19]
	v_lshlrev_b32_e32 v18, 16, v3
	v_and_b32_e32 v19, 0xffff0000, v3
	v_mul_f32_e32 v2, 0xbfb8aa3b, v18
	v_exp_f32_e32 v10, v2
	v_mul_f32_e32 v2, 0xbfb8aa3b, v19
	v_exp_f32_e32 v20, v2
	v_pk_mul_f32 v[2:3], v[16:17], v[8:9]
	v_add_f32_e32 v8, 1.0, v10
	v_rcp_f32_e32 v8, v8
	v_add_f32_e32 v9, 1.0, v20
	v_rcp_f32_e32 v9, v9
	v_lshlrev_b32_e32 v10, 16, v11
	v_and_b32_e32 v11, 0xffff0000, v11
	v_cvt_pk_bf16_f32 v2, v2, v3
	v_pk_mul_f32 v[8:9], v[8:9], v[18:19]
	s_lshl_b32 s34, s17, 1
	v_pk_mul_f32 v[8:9], v[8:9], v[10:11]
	v_lshlrev_b32_e32 v10, 16, v4
	v_and_b32_e32 v11, 0xffff0000, v4
	v_mul_f32_e32 v4, 0xbfb8aa3b, v10
	v_exp_f32_e32 v4, v4
	v_mul_f32_e32 v16, 0xbfb8aa3b, v11
	v_exp_f32_e32 v17, v16
	v_cvt_pk_bf16_f32 v3, v8, v9
	v_lshlrev_b64 v[8:9], 11, v[202:203]
	v_lshl_add_u64 v[8:9], s[82:83], 0, v[8:9]
	v_add_f32_e32 v4, 1.0, v4
	v_lshl_add_u64 v[8:9], v[8:9], 0, s[34:35]
	v_rcp_f32_e32 v16, v4
	v_add_f32_e32 v4, 1.0, v17
	v_lshl_add_u64 v[8:9], v[8:9], 0, v[96:97]
	v_rcp_f32_e32 v17, v4
	v_lshlrev_b32_e32 v4, 16, v5
	global_store_dwordx4 v[8:9], v[0:3], off offset:512 nt sc1
	v_and_b32_e32 v5, 0xffff0000, v5
	v_mul_f32_e32 v8, 0xbfb8aa3b, v4
	v_exp_f32_e32 v8, v8
	v_mul_f32_e32 v9, 0xbfb8aa3b, v5
	v_exp_f32_e32 v9, v9
	s_waitcnt lgkmcnt(0)
	v_lshlrev_b32_e32 v0, 16, v12
	v_and_b32_e32 v1, 0xffff0000, v12
	v_pk_mul_f32 v[2:3], v[16:17], v[10:11]
	s_add_i32 s67, s67, 1
	v_pk_mul_f32 v[0:1], v[2:3], v[0:1]
	v_add_f32_e32 v2, 1.0, v8
	v_rcp_f32_e32 v8, v2
	v_add_f32_e32 v2, 1.0, v9
	v_rcp_f32_e32 v9, v2
	v_cvt_pk_bf16_f32 v2, v0, v1
	v_lshlrev_b32_e32 v0, 16, v13
	v_and_b32_e32 v1, 0xffff0000, v13
	v_pk_mul_f32 v[4:5], v[8:9], v[4:5]
	v_lshlrev_b32_e32 v8, 16, v6
	v_and_b32_e32 v9, 0xffff0000, v6
	v_mul_f32_e32 v3, 0xbfb8aa3b, v8
	v_exp_f32_e32 v3, v3
	v_mul_f32_e32 v6, 0xbfb8aa3b, v9
	v_exp_f32_e32 v6, v6
	v_pk_mul_f32 v[0:1], v[4:5], v[0:1]
	v_add_f32_e32 v3, 1.0, v3
	v_rcp_f32_e32 v4, v3
	v_add_f32_e32 v3, 1.0, v6
	v_rcp_f32_e32 v5, v3
	v_lshlrev_b32_e32 v6, 16, v7
	v_and_b32_e32 v7, 0xffff0000, v7
	v_cvt_pk_bf16_f32 v3, v0, v1
	v_pk_mul_f32 v[4:5], v[4:5], v[8:9]
	v_mul_f32_e32 v8, 0xbfb8aa3b, v6
	v_exp_f32_e32 v8, v8
	v_mul_f32_e32 v9, 0xbfb8aa3b, v7
	v_exp_f32_e32 v9, v9
	v_lshlrev_b32_e32 v0, 16, v14
	v_and_b32_e32 v1, 0xffff0000, v14
	v_pk_mul_f32 v[0:1], v[4:5], v[0:1]
	v_add_f32_e32 v4, 1.0, v8
	v_rcp_f32_e32 v8, v4
	v_add_f32_e32 v4, 1.0, v9
	v_rcp_f32_e32 v9, v4
	v_cvt_pk_bf16_f32 v4, v0, v1
	v_lshlrev_b32_e32 v0, 16, v15
	v_and_b32_e32 v1, 0xffff0000, v15
	v_pk_mul_f32 v[6:7], v[8:9], v[6:7]
	s_cmp_eq_u32 s67, 4
	v_pk_mul_f32 v[0:1], v[6:7], v[0:1]
	s_nop 0
	v_cvt_pk_bf16_f32 v5, v0, v1
	v_or_b32_e32 v0, s50, v24
	v_mov_b32_e32 v1, s51
	v_lshlrev_b64 v[6:7], 11, v[0:1]
	v_lshl_add_u64 v[6:7], s[82:83], 0, v[6:7]
	v_lshl_add_u64 v[6:7], v[6:7], 0, s[34:35]
	v_lshl_add_u64 v[10:11], v[6:7], 0, v[96:97]
	ds_read_b128 v[6:9], v22 offset:2048
	global_store_dwordx4 v[10:11], v[2:5], off offset:512 nt sc1
	ds_read_b128 v[2:5], v22 offset:3072
	v_or_b32_e32 v0, 16, v211
	v_lshl_add_u32 v10, v0, 7, v23
	s_waitcnt lgkmcnt(1)
; __device__ __forceinline__ float bf_lo(unsigned w) { return __uint_as_float(w << 16); }
; __device__ __forceinline__ float silu_f(float v) { return v * __builtin_amdgcn_rcpf(1.0f + __builtin_amdgcn_exp2f(-1.4426950408889634f * v)); }
; __device__ __forceinline__ float bf_hi(unsigned w) { return __uint_as_float(w & 0xffff0000u); }
; __device__ __forceinline__ unsigned cvtpk_s(float lo,float hi){f32x2_t v={lo,hi};bf16x2_t b=__builtin_convertvector(v,bf16x2_t);return __builtin_bit_cast(unsigned,b);}
; template<int THRL> __device__ __forceinline__ void attn_unit(int b,int h,int qb,const bf16*Q,const bf16*__restrict__ K,const bf16*__restrict__ V,const unsigned short*GB,unsigned short*Y,const float*Fcum,int ts,char*shm){
;     ...
;     #pragma unroll
;     for(int i=0;i<4;++i){const int row=i*8+(lane>>3),ch=lane&7; const u32x4 v=*(const u32x4*)(stg+row*64+ch*8);
;       const u32x4 g=*(const u32x4*)(shm+LDS_G+wid*4096+i*1024+lane*16); u32x4 w;
;       w.x=cvtpk_s(bf_lo(v.x)*silu_f(bf_lo(g.x)),bf_hi(v.x)*silu_f(bf_hi(g.x))); w.y=cvtpk_s(bf_lo(v.y)*silu_f(bf_lo(g.y)),bf_hi(v.y)*silu_f(bf_hi(g.y)));
;       w.z=cvtpk_s(bf_lo(v.z)*silu_f(bf_lo(g.z)),bf_hi(v.z)*silu_f(bf_hi(g.z))); w.w=cvtpk_s(bf_lo(v.w)*silu_f(bf_lo(g.w)),bf_hi(v.w)*silu_f(bf_hi(g.w)));
;       *(u32x4*)(Y+(grow0+row)*1024+256+h*D+ch*8)=w;} }
;   asm volatile("s_waitcnt lgkmcnt(0)\n\ts_barrier":::"memory");
	v_lshlrev_b32_e32 v18, 16, v6
	v_and_b32_e32 v19, 0xffff0000, v6
	v_mul_f32_e32 v6, 0xbfb8aa3b, v18
	v_exp_f32_e32 v6, v6
	v_mul_f32_e32 v11, 0xbfb8aa3b, v19
	v_exp_f32_e32 v14, v11
	ds_read_b128 v[10:13], v10 offset:51200
	v_add_f32_e32 v6, 1.0, v6
	v_rcp_f32_e32 v20, v6
	v_add_f32_e32 v6, 1.0, v14
	v_rcp_f32_e32 v21, v6
	v_or_b32_e32 v24, 24, v211
	v_lshl_add_u32 v6, v24, 7, v23
	ds_read_b128 v[14:17], v6 offset:51200
	v_pk_mul_f32 v[18:19], v[20:21], v[18:19]
	v_lshlrev_b32_e32 v20, 16, v7
	v_and_b32_e32 v21, 0xffff0000, v7
	v_mul_f32_e32 v6, 0xbfb8aa3b, v20
	s_waitcnt lgkmcnt(1)
	v_lshlrev_b32_e32 v22, 16, v10
	v_and_b32_e32 v23, 0xffff0000, v10
	v_exp_f32_e32 v10, v6
	v_mul_f32_e32 v6, 0xbfb8aa3b, v21
	v_exp_f32_e32 v25, v6
	v_pk_mul_f32 v[6:7], v[18:19], v[22:23]
	v_add_f32_e32 v10, 1.0, v10
	v_rcp_f32_e32 v18, v10
	v_add_f32_e32 v10, 1.0, v25
	v_rcp_f32_e32 v19, v10
	v_cvt_pk_bf16_f32 v6, v6, v7
	v_lshlrev_b32_e32 v10, 16, v11
	v_and_b32_e32 v11, 0xffff0000, v11
	v_pk_mul_f32 v[18:19], v[18:19], v[20:21]
	v_lshlrev_b32_e32 v20, 16, v8
	v_and_b32_e32 v21, 0xffff0000, v8
	v_mul_f32_e32 v7, 0xbfb8aa3b, v20
	v_exp_f32_e32 v7, v7
	v_mul_f32_e32 v8, 0xbfb8aa3b, v21
	v_exp_f32_e32 v8, v8
	v_pk_mul_f32 v[10:11], v[18:19], v[10:11]
	v_add_f32_e32 v7, 1.0, v7
	v_rcp_f32_e32 v18, v7
	v_add_f32_e32 v7, 1.0, v8
	v_rcp_f32_e32 v19, v7
	v_cvt_pk_bf16_f32 v7, v10, v11
	v_lshlrev_b32_e32 v10, 16, v12
	v_and_b32_e32 v11, 0xffff0000, v12
	v_pk_mul_f32 v[18:19], v[18:19], v[20:21]
	v_lshlrev_b32_e32 v20, 16, v9
	v_and_b32_e32 v21, 0xffff0000, v9
	v_mul_f32_e32 v8, 0xbfb8aa3b, v20
	v_exp_f32_e32 v12, v8
	v_mul_f32_e32 v8, 0xbfb8aa3b, v21
	v_exp_f32_e32 v22, v8
	v_pk_mul_f32 v[8:9], v[18:19], v[10:11]
	v_add_f32_e32 v10, 1.0, v12
	v_rcp_f32_e32 v10, v10
	v_add_f32_e32 v11, 1.0, v22
	v_rcp_f32_e32 v11, v11
	v_lshlrev_b32_e32 v12, 16, v13
	v_and_b32_e32 v13, 0xffff0000, v13
	v_or_b32_e32 v0, s50, v0
	v_pk_mul_f32 v[10:11], v[10:11], v[20:21]
	v_cvt_pk_bf16_f32 v8, v8, v9
	v_pk_mul_f32 v[10:11], v[10:11], v[12:13]
	v_lshlrev_b32_e32 v12, 16, v2
	v_cvt_pk_bf16_f32 v9, v10, v11
	v_lshlrev_b64 v[10:11], 11, v[0:1]
	v_and_b32_e32 v13, 0xffff0000, v2
	v_mul_f32_e32 v0, 0xbfb8aa3b, v12
	v_exp_f32_e32 v0, v0
	v_mul_f32_e32 v2, 0xbfb8aa3b, v13
	v_exp_f32_e32 v2, v2
	v_lshl_add_u64 v[10:11], s[82:83], 0, v[10:11]
	v_add_f32_e32 v0, 1.0, v0
	v_lshl_add_u64 v[10:11], v[10:11], 0, s[34:35]
	v_rcp_f32_e32 v18, v0
	v_add_f32_e32 v0, 1.0, v2
	v_lshl_add_u64 v[10:11], v[10:11], 0, v[96:97]
	v_rcp_f32_e32 v19, v0
	global_store_dwordx4 v[10:11], v[6:9], off offset:512 nt sc1
	v_lshlrev_b32_e32 v10, 16, v3
	v_and_b32_e32 v11, 0xffff0000, v3
	v_mul_f32_e32 v0, 0xbfb8aa3b, v10
	v_exp_f32_e32 v0, v0
	v_mul_f32_e32 v2, 0xbfb8aa3b, v11
	v_pk_mul_f32 v[8:9], v[18:19], v[12:13]
	v_exp_f32_e32 v12, v2
	s_waitcnt lgkmcnt(0)
	v_lshlrev_b32_e32 v6, 16, v14
	v_and_b32_e32 v7, 0xffff0000, v14
	v_add_f32_e32 v0, 1.0, v0
	v_pk_mul_f32 v[2:3], v[8:9], v[6:7]
	v_rcp_f32_e32 v6, v0
	v_add_f32_e32 v0, 1.0, v12
	v_rcp_f32_e32 v7, v0
	v_cvt_pk_bf16_f32 v2, v2, v3
	v_lshlrev_b32_e32 v8, 16, v15
	v_and_b32_e32 v9, 0xffff0000, v15
	v_pk_mul_f32 v[6:7], v[6:7], v[10:11]
	v_lshlrev_b32_e32 v10, 16, v4
	v_and_b32_e32 v11, 0xffff0000, v4
	v_mul_f32_e32 v0, 0xbfb8aa3b, v10
	v_exp_f32_e32 v0, v0
	v_mul_f32_e32 v3, 0xbfb8aa3b, v11
	v_exp_f32_e32 v3, v3
	v_pk_mul_f32 v[6:7], v[6:7], v[8:9]
	v_add_f32_e32 v0, 1.0, v0
	v_rcp_f32_e32 v8, v0
	v_add_f32_e32 v0, 1.0, v3
	v_rcp_f32_e32 v9, v0
	v_cvt_pk_bf16_f32 v3, v6, v7
	v_lshlrev_b32_e32 v6, 16, v16
	v_and_b32_e32 v7, 0xffff0000, v16
	v_pk_mul_f32 v[8:9], v[8:9], v[10:11]
	v_lshlrev_b32_e32 v10, 16, v5
	v_and_b32_e32 v11, 0xffff0000, v5
	v_mul_f32_e32 v0, 0xbfb8aa3b, v10
	v_exp_f32_e32 v0, v0
	v_mul_f32_e32 v4, 0xbfb8aa3b, v11
	v_exp_f32_e32 v12, v4
	v_pk_mul_f32 v[4:5], v[8:9], v[6:7]
	v_add_f32_e32 v0, 1.0, v0
	v_rcp_f32_e32 v6, v0
	v_add_f32_e32 v0, 1.0, v12
	v_rcp_f32_e32 v7, v0
	v_or_b32_e32 v0, s50, v24
	v_lshlrev_b64 v[0:1], 11, v[0:1]
	v_lshlrev_b32_e32 v8, 16, v17
	v_and_b32_e32 v9, 0xffff0000, v17
	v_pk_mul_f32 v[6:7], v[6:7], v[10:11]
	v_lshl_add_u64 v[0:1], s[82:83], 0, v[0:1]
	v_pk_mul_f32 v[6:7], v[6:7], v[8:9]
	v_lshl_add_u64 v[0:1], v[0:1], 0, s[34:35]
	v_cvt_pk_bf16_f32 v4, v4, v5
	v_cvt_pk_bf16_f32 v5, v6, v7
	v_lshl_add_u64 v[0:1], v[0:1], 0, v[96:97]
	global_store_dwordx4 v[0:1], v[2:5], off offset:512 nt sc1
	s_waitcnt lgkmcnt(0)
	s_barrier
	s_cbranch_scc1 .LBB0_195
